# v12 + all five fp8 GEMM main loops: LDS-DMA loads in SGPR-base + 32-bit VGPR-offset form (16 fewer 64-bit VALU adds per iteration per wave)
# speedup vs baseline: 1.0059x; 1.0004x over previous
; #define PG8_STAGE(bufoff, gbase, voff) do { _Pragma("unroll") for (int _i = 0; _i < 2; ++_i) \
;         __builtin_amdgcn_global_load_lds((const unsigned*)((const char*)(gbase) + (voff)[_i]), (PG8_LAS unsigned*)(lds + (bufoff) + ldsw + _i * 8192), 16, 0, 0); } while (0)
; #define PG8_LDA(dst, b, h) do { _Pragma("unroll") for (int m = 0; m < 4; ++m) _Pragma("unroll") for (int k = 0; k < 2; ++k) dst[m][k] = *(const PG8_LAS bf16x8*)(lds + PG8_SA(b, h) + aoff + m * 2048 + k * 1024); } while (0)
; #define PG8_LDB(dst, b, h) do { _Pragma("unroll") for (int n = 0; n < 2; ++n) _Pragma("unroll") for (int k = 0; k < 2; ++k) dst[n][k] = *(const PG8_LAS bf16x8*)(lds + PG8_SB(b, h) + boff + n * 2048 + k * 1024); } while (0)
; #define PG8_WAIT_V(n) asm volatile("s_waitcnt vmcnt(" #n ")" ::: "memory")
; #define PG8_WAIT_L(n) asm volatile("s_waitcnt lgkmcnt(" #n ")" ::: "memory")
; #define PG8_BAR __builtin_amdgcn_s_barrier()
; #define PG8_SCHED __builtin_amdgcn_sched_barrier(0)
; #define PG8_BAR __builtin_amdgcn_s_barrier()
; template <class Epi, class Sched, bool ALIGN_EPI = false>
; __device__ __forceinline__ void gemm_phase8(PG8_LAS unsigned char* lds, const Gemm g, const Sched& S, const Epi& E) {
;     ...
;         for (int t = 0; t < nt; t += 2) {
;             const bool last = (t == nt - 2);
;             const char* a1 = cA + (size_t)(t + 1) * kstep;
;             const char* a2 = last ? nA : cA + (size_t)(t + 2) * kstep; const char* b2 = last ? nB : cB + (size_t)(t + 2) * kstep;
;             const char* a3 = a2 + kstep; const char* b3 = b2 + kstep;
;             if (last && has_next) S.a_ready(nxt);
;             PG8_LDB(B0, 0, 0); PG8_LDB(B1, 0, 1); PG8_SCHED; PG8_LDA(At, 0, 0); PG8_STAGE(PG8_SA(1, 1), a1 + hstepA, voffA);
;             PG8_WAIT_V(8); PG8_WAIT_L(0); PG8_BAR; PG8_MMA(0, 0, At, B0); PG8_MMA(0, 1, At, B1); PG8_BAR; PG8_SCHED;
;             PG8_LDA(At, 0, 1); PG8_STAGE(PG8_SB(0, 0), b2, voffB); PG8_STAGE(PG8_SB(0, 1), b2 + hstepB, voffB); PG8_STAGE(PG8_SA(0, 0), a2, voffA);
;             PG8_WAIT_V(8); PG8_WAIT_L(0); PG8_BAR; PG8_MMA(1, 0, At, B0); PG8_MMA(1, 1, At, B1); PG8_BAR; PG8_SCHED;
;             PG8_LDB(B0, 1, 0); PG8_LDB(B1, 1, 1); PG8_SCHED; PG8_LDA(At, 1, 0); PG8_STAGE(PG8_SA(0, 1), a2 + hstepA, voffA);
;             PG8_WAIT_V(8); PG8_WAIT_L(0); PG8_BAR; PG8_MMA(0, 0, At, B0); PG8_MMA(0, 1, At, B1); PG8_BAR; PG8_SCHED;
.LBB0_502:
	ds_read_b128 v[18:21], v187
	ds_read_b128 v[26:29], v187 offset:2048
	ds_read_b128 v[22:25], v188
	ds_read_b128 v[30:33], v188 offset:2048
	ds_read_b128 v[2:5], v189
	ds_read_b128 v[10:13], v189 offset:2048
	ds_read_b128 v[6:9], v190
	ds_read_b128 v[14:17], v190 offset:2048
	s_add_i32 s84, s34, 2
	s_add_u32 s30, s28, 0xfff50080
	s_addc_u32 s31, s29, -1
	s_cmp_eq_u32 s81, s34
	s_cselect_b32 s34, s20, s30
	s_cselect_b32 s35, s21, s31
	s_cselect_b32 s31, s23, s83
	s_cselect_b32 s30, s22, s82
	s_add_i32 m0, s54, 0xc000
	ds_read_b128 v[174:177], v191
	ds_read_b128 v[194:197], v191 offset:2048
	ds_read_b128 v[178:181], v192
	ds_read_b128 v[198:201], v192 offset:2048
	ds_read_b128 v[202:205], v191 offset:4096
	ds_read_b128 v[210:213], v191 offset:6144
	ds_read_b128 v[206:209], v192 offset:4096
	ds_read_b128 v[214:217], v192 offset:6144
	global_load_lds_dwordx4 v170, s[28:29]
	s_add_i32 m0, s54, 0xe000
	s_nop 0
	global_load_lds_dwordx4 v172, s[28:29]
	s_waitcnt vmcnt(8)
	s_waitcnt lgkmcnt(0)
	s_barrier
	s_setprio 1
	s_waitcnt lgkmcnt(0)
	s_cmp_eq_u32 s100, 1
	s_cbranch_scc1 .Lcy1_0f
	v_mfma_scale_f32_16x16x128_f8f6f4 v[158:161], v[18:25], v[174:181], v[158:161], v1, v182 op_sel_hi:[0,0,0]
	v_mfma_scale_f32_16x16x128_f8f6f4 v[154:157], v[26:33], v[174:181], v[154:157], v1, v182 op_sel_hi:[0,0,0]
	v_mfma_scale_f32_16x16x128_f8f6f4 v[142:145], v[18:25], v[194:201], v[142:145], v1, v182 op_sel_hi:[0,0,0]
	v_mfma_scale_f32_16x16x128_f8f6f4 v[138:141], v[26:33], v[194:201], v[138:141], v1, v182 op_sel_hi:[0,0,0]
	v_mfma_scale_f32_16x16x128_f8f6f4 v[126:129], v[18:25], v[202:209], v[126:129], v1, v182 op_sel_hi:[0,0,0]
	v_mfma_scale_f32_16x16x128_f8f6f4 v[122:125], v[26:33], v[202:209], v[122:125], v1, v182 op_sel_hi:[0,0,0]
	v_mfma_scale_f32_16x16x128_f8f6f4 v[110:113], v[18:25], v[210:217], v[110:113], v1, v182 op_sel_hi:[0,0,0]
	v_mfma_scale_f32_16x16x128_f8f6f4 v[106:109], v[26:33], v[210:217], v[106:109], v1, v182 op_sel_hi:[0,0,0]
	s_setprio 0
	s_setprio 1
	v_mfma_scale_f32_16x16x128_f8f6f4 v[150:153], v[2:9], v[174:181], v[150:153], v1, v182 op_sel_hi:[0,0,0]
	v_mfma_scale_f32_16x16x128_f8f6f4 v[146:149], v[10:17], v[174:181], v[146:149], v1, v182 op_sel_hi:[0,0,0]
	v_mfma_scale_f32_16x16x128_f8f6f4 v[134:137], v[2:9], v[194:201], v[134:137], v1, v182 op_sel_hi:[0,0,0]
	v_mfma_scale_f32_16x16x128_f8f6f4 v[130:133], v[10:17], v[194:201], v[130:133], v1, v182 op_sel_hi:[0,0,0]
	v_mfma_scale_f32_16x16x128_f8f6f4 v[118:121], v[2:9], v[202:209], v[118:121], v1, v182 op_sel_hi:[0,0,0]
	v_mfma_scale_f32_16x16x128_f8f6f4 v[114:117], v[10:17], v[202:209], v[114:117], v1, v182 op_sel_hi:[0,0,0]
	v_mfma_scale_f32_16x16x128_f8f6f4 v[102:105], v[2:9], v[210:217], v[102:105], v1, v182 op_sel_hi:[0,0,0]
	v_mfma_scale_f32_16x16x128_f8f6f4 v[98:101], v[10:17], v[210:217], v[98:101], v1, v182 op_sel_hi:[0,0,0]
.Lcy1_0j:
	s_setprio 0
	s_barrier
	s_add_i32 s85, s65, s53
	s_mov_b32 m0, s85
	ds_read_b128 v[194:197], v191 offset:16384
	ds_read_b128 v[202:205], v191 offset:18432
	ds_read_b128 v[198:201], v192 offset:16384
	ds_read_b128 v[206:209], v192 offset:18432
	ds_read_b128 v[210:213], v191 offset:20480
	ds_read_b128 v[218:221], v191 offset:22528
	ds_read_b128 v[214:217], v192 offset:20480
	ds_read_b128 v[222:225], v192 offset:22528
	global_load_lds_dwordx4 v164, s[30:31]
	s_add_i32 m0, s85, 0x2000
	s_add_u32 s88, s30, 0xb0000
	s_addc_u32 s89, s31, 0
	s_add_i32 s85, s66, s53
	global_load_lds_dwordx4 v168, s[30:31]
	s_mov_b32 m0, s85
	s_nop 0
	global_load_lds_dwordx4 v164, s[88:89]
	s_add_i32 m0, s85, 0x2000
	s_nop 0
	global_load_lds_dwordx4 v168, s[88:89]
	s_mov_b32 m0, s54
	s_nop 0
	global_load_lds_dwordx4 v162, s[34:35]
	s_mov_b32 m0, s55
	s_nop 0
	global_load_lds_dwordx4 v166, s[34:35]
	s_waitcnt vmcnt(8)
	s_waitcnt lgkmcnt(0)
	s_barrier
	s_setprio 1
	s_waitcnt lgkmcnt(0)
	s_cmp_eq_u32 s100, 1
	s_cbranch_scc1 .Lcy1_1f
	v_mfma_scale_f32_16x16x128_f8f6f4 v[94:97], v[18:25], v[194:201], v[94:97], v1, v182 op_sel_hi:[0,0,0]
	v_mfma_scale_f32_16x16x128_f8f6f4 v[90:93], v[26:33], v[194:201], v[90:93], v1, v182 op_sel_hi:[0,0,0]
	v_mfma_scale_f32_16x16x128_f8f6f4 v[78:81], v[18:25], v[202:209], v[78:81], v1, v182 op_sel_hi:[0,0,0]
	v_mfma_scale_f32_16x16x128_f8f6f4 v[74:77], v[26:33], v[202:209], v[74:77], v1, v182 op_sel_hi:[0,0,0]
	v_mfma_scale_f32_16x16x128_f8f6f4 v[62:65], v[18:25], v[210:217], v[62:65], v1, v182 op_sel_hi:[0,0,0]
	v_mfma_scale_f32_16x16x128_f8f6f4 v[58:61], v[26:33], v[210:217], v[58:61], v1, v182 op_sel_hi:[0,0,0]
	v_mfma_scale_f32_16x16x128_f8f6f4 v[46:49], v[18:25], v[218:225], v[46:49], v1, v182 op_sel_hi:[0,0,0]
	v_mfma_scale_f32_16x16x128_f8f6f4 v[42:45], v[26:33], v[218:225], v[42:45], v1, v182 op_sel_hi:[0,0,0]
	s_setprio 0
	s_setprio 1
	v_mfma_scale_f32_16x16x128_f8f6f4 v[86:89], v[2:9], v[194:201], v[86:89], v1, v182 op_sel_hi:[0,0,0]
	v_mfma_scale_f32_16x16x128_f8f6f4 v[82:85], v[10:17], v[194:201], v[82:85], v1, v182 op_sel_hi:[0,0,0]
	v_mfma_scale_f32_16x16x128_f8f6f4 v[70:73], v[2:9], v[202:209], v[70:73], v1, v182 op_sel_hi:[0,0,0]
	v_mfma_scale_f32_16x16x128_f8f6f4 v[66:69], v[10:17], v[202:209], v[66:69], v1, v182 op_sel_hi:[0,0,0]
	v_mfma_scale_f32_16x16x128_f8f6f4 v[54:57], v[2:9], v[210:217], v[54:57], v1, v182 op_sel_hi:[0,0,0]
	v_mfma_scale_f32_16x16x128_f8f6f4 v[50:53], v[10:17], v[210:217], v[50:53], v1, v182 op_sel_hi:[0,0,0]
	v_mfma_scale_f32_16x16x128_f8f6f4 v[38:41], v[2:9], v[218:225], v[38:41], v1, v182 op_sel_hi:[0,0,0]
	v_mfma_scale_f32_16x16x128_f8f6f4 v[34:37], v[10:17], v[218:225], v[34:37], v1, v182 op_sel_hi:[0,0,0]
; #define PG8_STAGE(bufoff, gbase, voff) do { _Pragma("unroll") for (int _i = 0; _i < 2; ++_i) \
;         __builtin_amdgcn_global_load_lds((const unsigned*)((const char*)(gbase) + (voff)[_i]), (PG8_LAS unsigned*)(lds + (bufoff) + ldsw + _i * 8192), 16, 0, 0); } while (0)
; #define PG8_LDA(dst, b, h) do { _Pragma("unroll") for (int m = 0; m < 4; ++m) _Pragma("unroll") for (int k = 0; k < 2; ++k) dst[m][k] = *(const PG8_LAS bf16x8*)(lds + PG8_SA(b, h) + aoff + m * 2048 + k * 1024); } while (0)
; #define PG8_LDB(dst, b, h) do { _Pragma("unroll") for (int n = 0; n < 2; ++n) _Pragma("unroll") for (int k = 0; k < 2; ++k) dst[n][k] = *(const PG8_LAS bf16x8*)(lds + PG8_SB(b, h) + boff + n * 2048 + k * 1024); } while (0)
; #define PG8_MMA(ai, bj, At, Bt) do { __builtin_amdgcn_s_setprio(1); _Pragma("unroll") for (int m = 0; m < 4; ++m) _Pragma("unroll") for (int n = 0; n < 2; ++n) _Pragma("unroll") for (int k = 0; k < 2; ++k) \
;         acc[ai][bj][m][n] = __builtin_amdgcn_mfma_f32_16x16x32_bf16(Bt[n][k], At[m][k], acc[ai][bj][m][n], 0, 0, 0); __builtin_amdgcn_s_setprio(0); } while (0)
; #define PG8_WAIT_V(n) asm volatile("s_waitcnt vmcnt(" #n ")" ::: "memory")
; #define PG8_WAIT_L(n) asm volatile("s_waitcnt lgkmcnt(" #n ")" ::: "memory")
; #define PG8_BAR __builtin_amdgcn_s_barrier()
; #define PG8_SCHED __builtin_amdgcn_sched_barrier(0)
; #define PG8_STAGE(bufoff, gbase, voff) do { _Pragma("unroll") for (int _i = 0; _i < 2; ++_i) \
;         __builtin_amdgcn_global_load_lds((const unsigned*)((const char*)(gbase) + (voff)[_i]), (PG8_LAS unsigned*)(lds + (bufoff) + ldsw + _i * 8192), 16, 0, 0); } while (0)
; #define PG8_BAR __builtin_amdgcn_s_barrier()
; template <class Epi, class Sched, bool ALIGN_EPI = false>
; __device__ __forceinline__ void gemm_phase8(PG8_LAS unsigned char* lds, const Gemm g, const Sched& S, const Epi& E) {
;     ...
;             PG8_LDB(B0, 1, 0); PG8_LDB(B1, 1, 1); PG8_SCHED; PG8_LDA(At, 1, 0); PG8_STAGE(PG8_SA(0, 1), a2 + hstepA, voffA);
;             PG8_WAIT_V(8); PG8_WAIT_L(0); PG8_BAR; PG8_MMA(0, 0, At, B0); PG8_MMA(0, 1, At, B1); PG8_BAR; PG8_SCHED;
;             PG8_LDA(At, 1, 1); PG8_STAGE(PG8_SB(1, 0), b3, voffB); PG8_STAGE(PG8_SB(1, 1), b3 + hstepB, voffB); PG8_STAGE(PG8_SA(1, 0), a3, voffA);
;             PG8_WAIT_V(8); PG8_WAIT_L(0); PG8_BAR; PG8_MMA(1, 0, At, B0); PG8_MMA(1, 1, At, B1); PG8_BAR; PG8_SCHED;
;         }
.Lcy1_1j:
	s_setprio 0
	s_barrier
	s_add_i32 s85, 0, 0x18000
	s_add_i32 s88, 0, 0x1c000
	v_add_u32_e32 v6, s85, v184
	v_add_u32_e32 v14, s85, v185
	v_add_u32_e32 v22, s88, v184
	v_add_u32_e32 v30, s88, v185
	ds_read_b128 v[2:5], v6
	ds_read_b128 v[10:13], v6 offset:2048
	ds_read_b128 v[6:9], v14
	ds_read_b128 v[14:17], v14 offset:2048
	ds_read_b128 v[18:21], v22
	ds_read_b128 v[26:29], v22 offset:2048
	ds_read_b128 v[22:25], v30
	ds_read_b128 v[30:33], v30 offset:2048
	s_add_u32 s34, s34, 0xb0000
	s_addc_u32 s35, s35, 0
	s_mov_b32 m0, s56
	ds_read_b128 v[194:197], v191 offset:32768
	ds_read_b128 v[202:205], v191 offset:34816
	ds_read_b128 v[198:201], v192 offset:32768
	ds_read_b128 v[206:209], v192 offset:34816
	ds_read_b128 v[210:213], v191 offset:36864
	ds_read_b128 v[218:221], v191 offset:38912
	ds_read_b128 v[214:217], v192 offset:36864
	ds_read_b128 v[222:225], v192 offset:38912
	global_load_lds_dwordx4 v162, s[34:35]
	s_mov_b32 m0, s57
	s_nop 0
	global_load_lds_dwordx4 v166, s[34:35]
	s_waitcnt vmcnt(8)
	s_waitcnt lgkmcnt(0)
	s_barrier
	s_setprio 1
	s_waitcnt lgkmcnt(0)
	v_mfma_scale_f32_16x16x128_f8f6f4 v[158:161], v[2:9], v[194:201], v[158:161], v1, v182 op_sel_hi:[0,0,0]
	v_mfma_scale_f32_16x16x128_f8f6f4 v[154:157], v[10:17], v[194:201], v[154:157], v1, v182 op_sel_hi:[0,0,0]
	v_mfma_scale_f32_16x16x128_f8f6f4 v[142:145], v[2:9], v[202:209], v[142:145], v1, v182 op_sel_hi:[0,0,0]
	v_mfma_scale_f32_16x16x128_f8f6f4 v[138:141], v[10:17], v[202:209], v[138:141], v1, v182 op_sel_hi:[0,0,0]
	v_mfma_scale_f32_16x16x128_f8f6f4 v[126:129], v[2:9], v[210:217], v[126:129], v1, v182 op_sel_hi:[0,0,0]
	v_mfma_scale_f32_16x16x128_f8f6f4 v[122:125], v[10:17], v[210:217], v[122:125], v1, v182 op_sel_hi:[0,0,0]
	v_mfma_scale_f32_16x16x128_f8f6f4 v[110:113], v[2:9], v[218:225], v[110:113], v1, v182 op_sel_hi:[0,0,0]
	v_mfma_scale_f32_16x16x128_f8f6f4 v[106:109], v[10:17], v[218:225], v[106:109], v1, v182 op_sel_hi:[0,0,0]
	s_setprio 0
	s_setprio 1
	v_mfma_scale_f32_16x16x128_f8f6f4 v[150:153], v[18:25], v[194:201], v[150:153], v1, v182 op_sel_hi:[0,0,0]
	v_mfma_scale_f32_16x16x128_f8f6f4 v[146:149], v[26:33], v[194:201], v[146:149], v1, v182 op_sel_hi:[0,0,0]
	v_mfma_scale_f32_16x16x128_f8f6f4 v[134:137], v[18:25], v[202:209], v[134:137], v1, v182 op_sel_hi:[0,0,0]
	v_mfma_scale_f32_16x16x128_f8f6f4 v[130:133], v[26:33], v[202:209], v[130:133], v1, v182 op_sel_hi:[0,0,0]
	v_mfma_scale_f32_16x16x128_f8f6f4 v[118:121], v[18:25], v[210:217], v[118:121], v1, v182 op_sel_hi:[0,0,0]
	v_mfma_scale_f32_16x16x128_f8f6f4 v[114:117], v[26:33], v[210:217], v[114:117], v1, v182 op_sel_hi:[0,0,0]
	v_mfma_scale_f32_16x16x128_f8f6f4 v[102:105], v[18:25], v[218:225], v[102:105], v1, v182 op_sel_hi:[0,0,0]
	v_mfma_scale_f32_16x16x128_f8f6f4 v[98:101], v[26:33], v[218:225], v[98:101], v1, v182 op_sel_hi:[0,0,0]
	s_setprio 0
	s_barrier
	s_add_i32 s101, s85, s53
	s_add_u32 s98, s30, s12
	s_addc_u32 s99, s31, s13
	s_mov_b32 m0, s101
	ds_read_b128 v[194:197], v191 offset:49152
	ds_read_b128 v[202:205], v191 offset:51200
	ds_read_b128 v[198:201], v192 offset:49152
	ds_read_b128 v[206:209], v192 offset:51200
	ds_read_b128 v[210:213], v191 offset:53248
	ds_read_b128 v[218:221], v191 offset:55296
	ds_read_b128 v[214:217], v192 offset:53248
	ds_read_b128 v[222:225], v192 offset:55296
	global_load_lds_dwordx4 v164, s[98:99]
	s_add_i32 m0, s101, 0x2000
	s_add_u32 s30, s30, 0xb0080
	s_addc_u32 s31, s31, 0
	s_add_i32 s101, s88, s53
	global_load_lds_dwordx4 v168, s[98:99]
	s_add_u32 s98, s34, s12
	s_addc_u32 s99, s35, s13
	s_sub_u32 s98, s98, 0xb0000
	s_subb_u32 s99, s99, 0
	s_mov_b32 m0, s101
	s_nop 0
	global_load_lds_dwordx4 v164, s[30:31]
	s_add_i32 m0, s101, 0x2000
	s_nop 0
	global_load_lds_dwordx4 v168, s[30:31]
	s_mov_b32 m0, s63
	s_nop 0
	global_load_lds_dwordx4 v162, s[98:99]
	s_mov_b32 m0, s64
	s_nop 0
	global_load_lds_dwordx4 v166, s[98:99]
	s_waitcnt vmcnt(8)
	s_waitcnt lgkmcnt(0)
	s_barrier
	s_setprio 1
	s_waitcnt lgkmcnt(0)
	v_mfma_scale_f32_16x16x128_f8f6f4 v[94:97], v[2:9], v[194:201], v[94:97], v1, v182 op_sel_hi:[0,0,0]
	v_mfma_scale_f32_16x16x128_f8f6f4 v[90:93], v[10:17], v[194:201], v[90:93], v1, v182 op_sel_hi:[0,0,0]
	v_mfma_scale_f32_16x16x128_f8f6f4 v[78:81], v[2:9], v[202:209], v[78:81], v1, v182 op_sel_hi:[0,0,0]
	v_mfma_scale_f32_16x16x128_f8f6f4 v[74:77], v[10:17], v[202:209], v[74:77], v1, v182 op_sel_hi:[0,0,0]
	v_mfma_scale_f32_16x16x128_f8f6f4 v[62:65], v[2:9], v[210:217], v[62:65], v1, v182 op_sel_hi:[0,0,0]
	v_mfma_scale_f32_16x16x128_f8f6f4 v[58:61], v[10:17], v[210:217], v[58:61], v1, v182 op_sel_hi:[0,0,0]
	v_mfma_scale_f32_16x16x128_f8f6f4 v[46:49], v[2:9], v[218:225], v[46:49], v1, v182 op_sel_hi:[0,0,0]
	v_mfma_scale_f32_16x16x128_f8f6f4 v[42:45], v[10:17], v[218:225], v[42:45], v1, v182 op_sel_hi:[0,0,0]
	s_setprio 0
	s_setprio 1
	v_mfma_scale_f32_16x16x128_f8f6f4 v[86:89], v[18:25], v[194:201], v[86:89], v1, v182 op_sel_hi:[0,0,0]
	v_mfma_scale_f32_16x16x128_f8f6f4 v[82:85], v[26:33], v[194:201], v[82:85], v1, v182 op_sel_hi:[0,0,0]
	v_mfma_scale_f32_16x16x128_f8f6f4 v[70:73], v[18:25], v[202:209], v[70:73], v1, v182 op_sel_hi:[0,0,0]
	v_mfma_scale_f32_16x16x128_f8f6f4 v[66:69], v[26:33], v[202:209], v[66:69], v1, v182 op_sel_hi:[0,0,0]
	v_mfma_scale_f32_16x16x128_f8f6f4 v[54:57], v[18:25], v[210:217], v[54:57], v1, v182 op_sel_hi:[0,0,0]
	v_mfma_scale_f32_16x16x128_f8f6f4 v[50:53], v[26:33], v[210:217], v[50:53], v1, v182 op_sel_hi:[0,0,0]
	v_mfma_scale_f32_16x16x128_f8f6f4 v[38:41], v[18:25], v[218:225], v[38:41], v1, v182 op_sel_hi:[0,0,0]
	v_mfma_scale_f32_16x16x128_f8f6f4 v[34:37], v[26:33], v[218:225], v[34:37], v1, v182 op_sel_hi:[0,0,0]
	s_setprio 0
	s_barrier
	s_add_u32 s28, s28, 0x100
	s_addc_u32 s29, s29, 0
	s_add_u32 s82, s82, 0x100
	s_addc_u32 s83, s83, 0
	s_cmp_ge_u32 s84, s25
	s_mov_b32 s34, s84
	s_cbranch_scc0 .LBB0_502
	s_and_b64 vcc, exec, s[14:15]
	s_cbranch_vccz .LBB0_505
	s_barrier

; #define PG8_STAGE(bufoff, gbase, voff) do { _Pragma("unroll") for (int _i = 0; _i < 2; ++_i) \
;         __builtin_amdgcn_global_load_lds((const unsigned*)((const char*)(gbase) + (voff)[_i]), (PG8_LAS unsigned*)(lds + (bufoff) + ldsw + _i * 8192), 16, 0, 0); } while (0)
; #define PG8_LDA(dst, b, h) do { _Pragma("unroll") for (int m = 0; m < 4; ++m) _Pragma("unroll") for (int k = 0; k < 2; ++k) dst[m][k] = *(const PG8_LAS bf16x8*)(lds + PG8_SA(b, h) + aoff + m * 2048 + k * 1024); } while (0)
; #define PG8_LDB(dst, b, h) do { _Pragma("unroll") for (int n = 0; n < 2; ++n) _Pragma("unroll") for (int k = 0; k < 2; ++k) dst[n][k] = *(const PG8_LAS bf16x8*)(lds + PG8_SB(b, h) + boff + n * 2048 + k * 1024); } while (0)
; #define PG8_WAIT_V(n) asm volatile("s_waitcnt vmcnt(" #n ")" ::: "memory")
; #define PG8_WAIT_L(n) asm volatile("s_waitcnt lgkmcnt(" #n ")" ::: "memory")
; #define PG8_BAR __builtin_amdgcn_s_barrier()
; #define PG8_SCHED __builtin_amdgcn_sched_barrier(0)
; #define PG8_BAR __builtin_amdgcn_s_barrier()
; template <class Epi, class Sched, bool ALIGN_EPI = false>
; __device__ __forceinline__ void gemm_phase8(PG8_LAS unsigned char* lds, const Gemm g, const Sched& S, const Epi& E) {
;     ...
;         for (int t = 0; t < nt; t += 2) {
;             const bool last = (t == nt - 2);
;             const char* a1 = cA + (size_t)(t + 1) * kstep;
;             const char* a2 = last ? nA : cA + (size_t)(t + 2) * kstep; const char* b2 = last ? nB : cB + (size_t)(t + 2) * kstep;
;             const char* a3 = a2 + kstep; const char* b3 = b2 + kstep;
;             if (last && has_next) S.a_ready(nxt);
;             PG8_LDB(B0, 0, 0); PG8_LDB(B1, 0, 1); PG8_SCHED; PG8_LDA(At, 0, 0); PG8_STAGE(PG8_SA(1, 1), a1 + hstepA, voffA);
;             PG8_WAIT_V(8); PG8_WAIT_L(0); PG8_BAR; PG8_MMA(0, 0, At, B0); PG8_MMA(0, 1, At, B1); PG8_BAR; PG8_SCHED;
;             PG8_LDA(At, 0, 1); PG8_STAGE(PG8_SB(0, 0), b2, voffB); PG8_STAGE(PG8_SB(0, 1), b2 + hstepB, voffB); PG8_STAGE(PG8_SA(0, 0), a2, voffA);
;             PG8_WAIT_V(8); PG8_WAIT_L(0); PG8_BAR; PG8_MMA(1, 0, At, B0); PG8_MMA(1, 1, At, B1); PG8_BAR; PG8_SCHED;
;             PG8_LDB(B0, 1, 0); PG8_LDB(B1, 1, 1); PG8_SCHED; PG8_LDA(At, 1, 0); PG8_STAGE(PG8_SA(0, 1), a2 + hstepA, voffA);
;             PG8_WAIT_V(8); PG8_WAIT_L(0); PG8_BAR; PG8_MMA(0, 0, At, B0); PG8_MMA(0, 1, At, B1); PG8_BAR; PG8_SCHED;
.LBB0_1187:
	ds_read_b128 v[18:21], v187
	ds_read_b128 v[26:29], v187 offset:2048
	ds_read_b128 v[22:25], v188
	ds_read_b128 v[30:33], v188 offset:2048
	ds_read_b128 v[2:5], v189
	ds_read_b128 v[10:13], v189 offset:2048
	ds_read_b128 v[6:9], v190
	ds_read_b128 v[14:17], v190 offset:2048
	s_add_i32 s80, s58, 2
	s_add_u32 s34, s56, 0xfffc0080
	s_addc_u32 s35, s57, -1
	s_cmp_eq_u32 s77, s58
	s_cselect_b32 s58, s31, s34
	s_cselect_b32 s59, s19, s35
	s_cselect_b32 s35, s21, s79
	s_cselect_b32 s34, s75, s78
	s_add_i32 m0, s29, 0xc000
	ds_read_b128 v[174:177], v191
	ds_read_b128 v[194:197], v191 offset:2048
	ds_read_b128 v[178:181], v192
	ds_read_b128 v[198:201], v192 offset:2048
	ds_read_b128 v[202:205], v191 offset:4096
	ds_read_b128 v[210:213], v191 offset:6144
	ds_read_b128 v[206:209], v192 offset:4096
	ds_read_b128 v[214:217], v192 offset:6144
	global_load_lds_dwordx4 v170, s[56:57]
	s_add_i32 m0, s29, 0xe000
	s_nop 0
	global_load_lds_dwordx4 v172, s[56:57]
	s_waitcnt vmcnt(8)
	s_waitcnt lgkmcnt(0)
	s_barrier
	s_setprio 1
	s_waitcnt lgkmcnt(0)
	s_cmp_eq_u32 s100, 1
	s_cbranch_scc1 .Lcy3_0f
	v_mfma_scale_f32_16x16x128_f8f6f4 v[158:161], v[18:25], v[174:181], v[158:161], v1, v182 op_sel_hi:[0,0,0]
	v_mfma_scale_f32_16x16x128_f8f6f4 v[154:157], v[26:33], v[174:181], v[154:157], v1, v182 op_sel_hi:[0,0,0]
	v_mfma_scale_f32_16x16x128_f8f6f4 v[150:153], v[18:25], v[194:201], v[150:153], v1, v182 op_sel_hi:[0,0,0]
	v_mfma_scale_f32_16x16x128_f8f6f4 v[138:141], v[26:33], v[194:201], v[138:141], v1, v182 op_sel_hi:[0,0,0]
	v_mfma_scale_f32_16x16x128_f8f6f4 v[130:133], v[18:25], v[202:209], v[130:133], v1, v182 op_sel_hi:[0,0,0]
	v_mfma_scale_f32_16x16x128_f8f6f4 v[122:125], v[26:33], v[202:209], v[122:125], v1, v182 op_sel_hi:[0,0,0]
	v_mfma_scale_f32_16x16x128_f8f6f4 v[118:121], v[18:25], v[210:217], v[118:121], v1, v182 op_sel_hi:[0,0,0]
	v_mfma_scale_f32_16x16x128_f8f6f4 v[106:109], v[26:33], v[210:217], v[106:109], v1, v182 op_sel_hi:[0,0,0]
	s_setprio 0
	s_setprio 1
	v_mfma_scale_f32_16x16x128_f8f6f4 v[146:149], v[2:9], v[174:181], v[146:149], v1, v182 op_sel_hi:[0,0,0]
	v_mfma_scale_f32_16x16x128_f8f6f4 v[142:145], v[10:17], v[174:181], v[142:145], v1, v182 op_sel_hi:[0,0,0]
	v_mfma_scale_f32_16x16x128_f8f6f4 v[134:137], v[2:9], v[194:201], v[134:137], v1, v182 op_sel_hi:[0,0,0]
	v_mfma_scale_f32_16x16x128_f8f6f4 v[126:129], v[10:17], v[194:201], v[126:129], v1, v182 op_sel_hi:[0,0,0]
	v_mfma_scale_f32_16x16x128_f8f6f4 v[114:117], v[2:9], v[202:209], v[114:117], v1, v182 op_sel_hi:[0,0,0]
	v_mfma_scale_f32_16x16x128_f8f6f4 v[110:113], v[10:17], v[202:209], v[110:113], v1, v182 op_sel_hi:[0,0,0]
	v_mfma_scale_f32_16x16x128_f8f6f4 v[102:105], v[2:9], v[210:217], v[102:105], v1, v182 op_sel_hi:[0,0,0]
	v_mfma_scale_f32_16x16x128_f8f6f4 v[98:101], v[10:17], v[210:217], v[98:101], v1, v182 op_sel_hi:[0,0,0]
.Lcy3_0j:
	s_setprio 0
	s_barrier
	s_add_i32 s81, s71, s61
	s_mov_b32 m0, s81
	ds_read_b128 v[194:197], v191 offset:16384
	ds_read_b128 v[202:205], v191 offset:18432
	ds_read_b128 v[198:201], v192 offset:16384
	ds_read_b128 v[206:209], v192 offset:18432
	ds_read_b128 v[210:213], v191 offset:20480
	ds_read_b128 v[218:221], v191 offset:22528
	ds_read_b128 v[214:217], v192 offset:20480
	ds_read_b128 v[222:225], v192 offset:22528
	global_load_lds_dwordx4 v164, s[34:35]
	s_add_i32 m0, s81, 0x2000
	s_add_u32 s82, s34, 0x40000
	s_addc_u32 s83, s35, 0
	s_add_i32 s81, s72, s61
	global_load_lds_dwordx4 v168, s[34:35]
	s_mov_b32 m0, s81
	s_nop 0
	global_load_lds_dwordx4 v164, s[82:83]
	s_add_i32 m0, s81, 0x2000
	s_nop 0
	global_load_lds_dwordx4 v168, s[82:83]
	s_mov_b32 m0, s29
	s_nop 0
	global_load_lds_dwordx4 v162, s[58:59]
	s_mov_b32 m0, s53
	s_nop 0
	global_load_lds_dwordx4 v166, s[58:59]
	s_waitcnt vmcnt(8)
	s_waitcnt lgkmcnt(0)
	s_barrier
	s_setprio 1
	s_waitcnt lgkmcnt(0)
	s_cmp_eq_u32 s100, 1
	s_cbranch_scc1 .Lcy3_1f
	v_mfma_scale_f32_16x16x128_f8f6f4 v[94:97], v[18:25], v[194:201], v[94:97], v1, v182 op_sel_hi:[0,0,0]
	v_mfma_scale_f32_16x16x128_f8f6f4 v[90:93], v[26:33], v[194:201], v[90:93], v1, v182 op_sel_hi:[0,0,0]
	v_mfma_scale_f32_16x16x128_f8f6f4 v[82:85], v[18:25], v[202:209], v[82:85], v1, v182 op_sel_hi:[0,0,0]
	v_mfma_scale_f32_16x16x128_f8f6f4 v[74:77], v[26:33], v[202:209], v[74:77], v1, v182 op_sel_hi:[0,0,0]
	v_mfma_scale_f32_16x16x128_f8f6f4 v[66:69], v[18:25], v[210:217], v[66:69], v1, v182 op_sel_hi:[0,0,0]
	v_mfma_scale_f32_16x16x128_f8f6f4 v[58:61], v[26:33], v[210:217], v[58:61], v1, v182 op_sel_hi:[0,0,0]
	v_mfma_scale_f32_16x16x128_f8f6f4 v[50:53], v[18:25], v[218:225], v[50:53], v1, v182 op_sel_hi:[0,0,0]
	v_mfma_scale_f32_16x16x128_f8f6f4 v[42:45], v[26:33], v[218:225], v[42:45], v1, v182 op_sel_hi:[0,0,0]
	s_setprio 0
	s_setprio 1
	v_mfma_scale_f32_16x16x128_f8f6f4 v[86:89], v[2:9], v[194:201], v[86:89], v1, v182 op_sel_hi:[0,0,0]
	v_mfma_scale_f32_16x16x128_f8f6f4 v[78:81], v[10:17], v[194:201], v[78:81], v1, v182 op_sel_hi:[0,0,0]
	v_mfma_scale_f32_16x16x128_f8f6f4 v[70:73], v[2:9], v[202:209], v[70:73], v1, v182 op_sel_hi:[0,0,0]
	v_mfma_scale_f32_16x16x128_f8f6f4 v[62:65], v[10:17], v[202:209], v[62:65], v1, v182 op_sel_hi:[0,0,0]
	v_mfma_scale_f32_16x16x128_f8f6f4 v[54:57], v[2:9], v[210:217], v[54:57], v1, v182 op_sel_hi:[0,0,0]
	v_mfma_scale_f32_16x16x128_f8f6f4 v[46:49], v[10:17], v[210:217], v[46:49], v1, v182 op_sel_hi:[0,0,0]
	v_mfma_scale_f32_16x16x128_f8f6f4 v[38:41], v[2:9], v[218:225], v[38:41], v1, v182 op_sel_hi:[0,0,0]
	v_mfma_scale_f32_16x16x128_f8f6f4 v[34:37], v[10:17], v[218:225], v[34:37], v1, v182 op_sel_hi:[0,0,0]
; #define PG8_STAGE(bufoff, gbase, voff) do { _Pragma("unroll") for (int _i = 0; _i < 2; ++_i) \
;         __builtin_amdgcn_global_load_lds((const unsigned*)((const char*)(gbase) + (voff)[_i]), (PG8_LAS unsigned*)(lds + (bufoff) + ldsw + _i * 8192), 16, 0, 0); } while (0)
; #define PG8_LDA(dst, b, h) do { _Pragma("unroll") for (int m = 0; m < 4; ++m) _Pragma("unroll") for (int k = 0; k < 2; ++k) dst[m][k] = *(const PG8_LAS bf16x8*)(lds + PG8_SA(b, h) + aoff + m * 2048 + k * 1024); } while (0)
; #define PG8_LDB(dst, b, h) do { _Pragma("unroll") for (int n = 0; n < 2; ++n) _Pragma("unroll") for (int k = 0; k < 2; ++k) dst[n][k] = *(const PG8_LAS bf16x8*)(lds + PG8_SB(b, h) + boff + n * 2048 + k * 1024); } while (0)
; #define PG8_MMA(ai, bj, At, Bt) do { __builtin_amdgcn_s_setprio(1); _Pragma("unroll") for (int m = 0; m < 4; ++m) _Pragma("unroll") for (int n = 0; n < 2; ++n) _Pragma("unroll") for (int k = 0; k < 2; ++k) \
;         acc[ai][bj][m][n] = __builtin_amdgcn_mfma_f32_16x16x32_bf16(Bt[n][k], At[m][k], acc[ai][bj][m][n], 0, 0, 0); __builtin_amdgcn_s_setprio(0); } while (0)
; #define PG8_WAIT_V(n) asm volatile("s_waitcnt vmcnt(" #n ")" ::: "memory")
; #define PG8_WAIT_L(n) asm volatile("s_waitcnt lgkmcnt(" #n ")" ::: "memory")
; #define PG8_BAR __builtin_amdgcn_s_barrier()
; #define PG8_SCHED __builtin_amdgcn_sched_barrier(0)
; #define PG8_STAGE(bufoff, gbase, voff) do { _Pragma("unroll") for (int _i = 0; _i < 2; ++_i) \
;         __builtin_amdgcn_global_load_lds((const unsigned*)((const char*)(gbase) + (voff)[_i]), (PG8_LAS unsigned*)(lds + (bufoff) + ldsw + _i * 8192), 16, 0, 0); } while (0)
; #define PG8_BAR __builtin_amdgcn_s_barrier()
; template <class Epi, class Sched, bool ALIGN_EPI = false>
; __device__ __forceinline__ void gemm_phase8(PG8_LAS unsigned char* lds, const Gemm g, const Sched& S, const Epi& E) {
;     ...
;             PG8_LDB(B0, 1, 0); PG8_LDB(B1, 1, 1); PG8_SCHED; PG8_LDA(At, 1, 0); PG8_STAGE(PG8_SA(0, 1), a2 + hstepA, voffA);
;             PG8_WAIT_V(8); PG8_WAIT_L(0); PG8_BAR; PG8_MMA(0, 0, At, B0); PG8_MMA(0, 1, At, B1); PG8_BAR; PG8_SCHED;
;             PG8_LDA(At, 1, 1); PG8_STAGE(PG8_SB(1, 0), b3, voffB); PG8_STAGE(PG8_SB(1, 1), b3 + hstepB, voffB); PG8_STAGE(PG8_SA(1, 0), a3, voffA);
;             PG8_WAIT_V(8); PG8_WAIT_L(0); PG8_BAR; PG8_MMA(1, 0, At, B0); PG8_MMA(1, 1, At, B1); PG8_BAR; PG8_SCHED;
;         }
.Lcy3_1j:
	s_setprio 0
	s_barrier
	s_add_i32 s81, 0, 0x18000
	s_add_i32 s82, 0, 0x1c000
	v_add_u32_e32 v6, s81, v184
	v_add_u32_e32 v14, s81, v185
	v_add_u32_e32 v22, s82, v184
	v_add_u32_e32 v30, s82, v185
	ds_read_b128 v[2:5], v6
	ds_read_b128 v[10:13], v6 offset:2048
	ds_read_b128 v[6:9], v14
	ds_read_b128 v[14:17], v14 offset:2048
	ds_read_b128 v[18:21], v22
	ds_read_b128 v[26:29], v22 offset:2048
	ds_read_b128 v[22:25], v30
	ds_read_b128 v[30:33], v30 offset:2048
	s_add_u32 s58, s58, 0x40000
	s_addc_u32 s59, s59, 0
	s_mov_b32 m0, s62
	ds_read_b128 v[194:197], v191 offset:32768
	ds_read_b128 v[202:205], v191 offset:34816
	ds_read_b128 v[198:201], v192 offset:32768
	ds_read_b128 v[206:209], v192 offset:34816
	ds_read_b128 v[210:213], v191 offset:36864
	ds_read_b128 v[218:221], v191 offset:38912
	ds_read_b128 v[214:217], v192 offset:36864
	ds_read_b128 v[222:225], v192 offset:38912
	global_load_lds_dwordx4 v162, s[58:59]
	s_mov_b32 m0, s63
	s_nop 0
	global_load_lds_dwordx4 v166, s[58:59]
	s_waitcnt vmcnt(8)
	s_waitcnt lgkmcnt(0)
	s_barrier
	s_setprio 1
	s_waitcnt lgkmcnt(0)
	v_mfma_scale_f32_16x16x128_f8f6f4 v[158:161], v[2:9], v[194:201], v[158:161], v1, v182 op_sel_hi:[0,0,0]
	v_mfma_scale_f32_16x16x128_f8f6f4 v[154:157], v[10:17], v[194:201], v[154:157], v1, v182 op_sel_hi:[0,0,0]
	v_mfma_scale_f32_16x16x128_f8f6f4 v[150:153], v[2:9], v[202:209], v[150:153], v1, v182 op_sel_hi:[0,0,0]
	v_mfma_scale_f32_16x16x128_f8f6f4 v[138:141], v[10:17], v[202:209], v[138:141], v1, v182 op_sel_hi:[0,0,0]
	v_mfma_scale_f32_16x16x128_f8f6f4 v[130:133], v[2:9], v[210:217], v[130:133], v1, v182 op_sel_hi:[0,0,0]
	v_mfma_scale_f32_16x16x128_f8f6f4 v[122:125], v[10:17], v[210:217], v[122:125], v1, v182 op_sel_hi:[0,0,0]
	v_mfma_scale_f32_16x16x128_f8f6f4 v[118:121], v[2:9], v[218:225], v[118:121], v1, v182 op_sel_hi:[0,0,0]
	v_mfma_scale_f32_16x16x128_f8f6f4 v[106:109], v[10:17], v[218:225], v[106:109], v1, v182 op_sel_hi:[0,0,0]
	s_setprio 0
	s_setprio 1
	v_mfma_scale_f32_16x16x128_f8f6f4 v[146:149], v[18:25], v[194:201], v[146:149], v1, v182 op_sel_hi:[0,0,0]
	v_mfma_scale_f32_16x16x128_f8f6f4 v[142:145], v[26:33], v[194:201], v[142:145], v1, v182 op_sel_hi:[0,0,0]
	v_mfma_scale_f32_16x16x128_f8f6f4 v[134:137], v[18:25], v[202:209], v[134:137], v1, v182 op_sel_hi:[0,0,0]
	v_mfma_scale_f32_16x16x128_f8f6f4 v[126:129], v[26:33], v[202:209], v[126:129], v1, v182 op_sel_hi:[0,0,0]
	v_mfma_scale_f32_16x16x128_f8f6f4 v[114:117], v[18:25], v[210:217], v[114:117], v1, v182 op_sel_hi:[0,0,0]
	v_mfma_scale_f32_16x16x128_f8f6f4 v[110:113], v[26:33], v[210:217], v[110:113], v1, v182 op_sel_hi:[0,0,0]
	v_mfma_scale_f32_16x16x128_f8f6f4 v[102:105], v[18:25], v[218:225], v[102:105], v1, v182 op_sel_hi:[0,0,0]
	v_mfma_scale_f32_16x16x128_f8f6f4 v[98:101], v[26:33], v[218:225], v[98:101], v1, v182 op_sel_hi:[0,0,0]
	s_setprio 0
	s_barrier
	s_add_i32 s101, s81, s61
	s_add_u32 s98, s34, s10
	s_addc_u32 s99, s35, s11
	s_mov_b32 m0, s101
	ds_read_b128 v[194:197], v191 offset:49152
	ds_read_b128 v[202:205], v191 offset:51200
	ds_read_b128 v[198:201], v192 offset:49152
	ds_read_b128 v[206:209], v192 offset:51200
	ds_read_b128 v[210:213], v191 offset:53248
	ds_read_b128 v[218:221], v191 offset:55296
	ds_read_b128 v[214:217], v192 offset:53248
	ds_read_b128 v[222:225], v192 offset:55296
	global_load_lds_dwordx4 v164, s[98:99]
	s_add_i32 m0, s101, 0x2000
	s_add_u32 s34, s34, 0x40080
	s_addc_u32 s35, s35, 0
	s_add_i32 s101, s82, s61
	global_load_lds_dwordx4 v168, s[98:99]
	s_add_u32 s98, s58, s10
	s_addc_u32 s99, s59, s11
	s_sub_u32 s98, s98, 0x40000
	s_subb_u32 s99, s99, 0
	s_mov_b32 m0, s101
	s_nop 0
	global_load_lds_dwordx4 v164, s[34:35]
	s_add_i32 m0, s101, 0x2000
	s_nop 0
	global_load_lds_dwordx4 v168, s[34:35]
	s_mov_b32 m0, s69
	s_nop 0
	global_load_lds_dwordx4 v162, s[98:99]
	s_mov_b32 m0, s70
	s_nop 0
	global_load_lds_dwordx4 v166, s[98:99]
	s_waitcnt vmcnt(8)
	s_waitcnt lgkmcnt(0)
	s_barrier
	s_setprio 1
	s_waitcnt lgkmcnt(0)
	v_mfma_scale_f32_16x16x128_f8f6f4 v[94:97], v[2:9], v[194:201], v[94:97], v1, v182 op_sel_hi:[0,0,0]
	v_mfma_scale_f32_16x16x128_f8f6f4 v[90:93], v[10:17], v[194:201], v[90:93], v1, v182 op_sel_hi:[0,0,0]
	v_mfma_scale_f32_16x16x128_f8f6f4 v[82:85], v[2:9], v[202:209], v[82:85], v1, v182 op_sel_hi:[0,0,0]
	v_mfma_scale_f32_16x16x128_f8f6f4 v[74:77], v[10:17], v[202:209], v[74:77], v1, v182 op_sel_hi:[0,0,0]
	v_mfma_scale_f32_16x16x128_f8f6f4 v[66:69], v[2:9], v[210:217], v[66:69], v1, v182 op_sel_hi:[0,0,0]
	v_mfma_scale_f32_16x16x128_f8f6f4 v[58:61], v[10:17], v[210:217], v[58:61], v1, v182 op_sel_hi:[0,0,0]
	v_mfma_scale_f32_16x16x128_f8f6f4 v[50:53], v[2:9], v[218:225], v[50:53], v1, v182 op_sel_hi:[0,0,0]
	v_mfma_scale_f32_16x16x128_f8f6f4 v[42:45], v[10:17], v[218:225], v[42:45], v1, v182 op_sel_hi:[0,0,0]
	s_setprio 0
	s_setprio 1
	v_mfma_scale_f32_16x16x128_f8f6f4 v[86:89], v[18:25], v[194:201], v[86:89], v1, v182 op_sel_hi:[0,0,0]
	v_mfma_scale_f32_16x16x128_f8f6f4 v[78:81], v[26:33], v[194:201], v[78:81], v1, v182 op_sel_hi:[0,0,0]
	v_mfma_scale_f32_16x16x128_f8f6f4 v[70:73], v[18:25], v[202:209], v[70:73], v1, v182 op_sel_hi:[0,0,0]
	v_mfma_scale_f32_16x16x128_f8f6f4 v[62:65], v[26:33], v[202:209], v[62:65], v1, v182 op_sel_hi:[0,0,0]
	v_mfma_scale_f32_16x16x128_f8f6f4 v[54:57], v[18:25], v[210:217], v[54:57], v1, v182 op_sel_hi:[0,0,0]
	v_mfma_scale_f32_16x16x128_f8f6f4 v[46:49], v[26:33], v[210:217], v[46:49], v1, v182 op_sel_hi:[0,0,0]
	v_mfma_scale_f32_16x16x128_f8f6f4 v[38:41], v[18:25], v[218:225], v[38:41], v1, v182 op_sel_hi:[0,0,0]
	v_mfma_scale_f32_16x16x128_f8f6f4 v[34:37], v[26:33], v[218:225], v[34:37], v1, v182 op_sel_hi:[0,0,0]
	s_setprio 0
	s_barrier
	s_add_u32 s56, s56, 0x100
	s_addc_u32 s57, s57, 0
	s_add_u32 s78, s78, 0x100
	s_addc_u32 s79, s79, 0
	s_cmp_ge_u32 s80, s76
	s_mov_b32 s58, s80
	s_cbranch_scc0 .LBB0_1187
	s_and_b64 vcc, exec, s[12:13]
	s_cbranch_vccz .LBB0_1190
	s_barrier

; #define PG8_STAGE(bufoff, gbase, voff) do { _Pragma("unroll") for (int _i = 0; _i < 2; ++_i) \
;         __builtin_amdgcn_global_load_lds((const unsigned*)((const char*)(gbase) + (voff)[_i]), (PG8_LAS unsigned*)(lds + (bufoff) + ldsw + _i * 8192), 16, 0, 0); } while (0)
; #define PG8_LDA(dst, b, h) do { _Pragma("unroll") for (int m = 0; m < 4; ++m) _Pragma("unroll") for (int k = 0; k < 2; ++k) dst[m][k] = *(const PG8_LAS bf16x8*)(lds + PG8_SA(b, h) + aoff + m * 2048 + k * 1024); } while (0)
; #define PG8_LDB(dst, b, h) do { _Pragma("unroll") for (int n = 0; n < 2; ++n) _Pragma("unroll") for (int k = 0; k < 2; ++k) dst[n][k] = *(const PG8_LAS bf16x8*)(lds + PG8_SB(b, h) + boff + n * 2048 + k * 1024); } while (0)
; #define PG8_WAIT_V(n) asm volatile("s_waitcnt vmcnt(" #n ")" ::: "memory")
; #define PG8_WAIT_L(n) asm volatile("s_waitcnt lgkmcnt(" #n ")" ::: "memory")
; #define PG8_BAR __builtin_amdgcn_s_barrier()
; #define PG8_SCHED __builtin_amdgcn_sched_barrier(0)
; #define PG8_BAR __builtin_amdgcn_s_barrier()
; template <class Epi, class Sched, bool ALIGN_EPI = false>
; __device__ __forceinline__ void gemm_phase8(PG8_LAS unsigned char* lds, const Gemm g, const Sched& S, const Epi& E) {
;     ...
;         for (int t = 0; t < nt; t += 2) {
;             const bool last = (t == nt - 2);
;             const char* a1 = cA + (size_t)(t + 1) * kstep;
;             const char* a2 = last ? nA : cA + (size_t)(t + 2) * kstep; const char* b2 = last ? nB : cB + (size_t)(t + 2) * kstep;
;             const char* a3 = a2 + kstep; const char* b3 = b2 + kstep;
;             if (last && has_next) S.a_ready(nxt);
;             PG8_LDB(B0, 0, 0); PG8_LDB(B1, 0, 1); PG8_SCHED; PG8_LDA(At, 0, 0); PG8_STAGE(PG8_SA(1, 1), a1 + hstepA, voffA);
;             PG8_WAIT_V(8); PG8_WAIT_L(0); PG8_BAR; PG8_MMA(0, 0, At, B0); PG8_MMA(0, 1, At, B1); PG8_BAR; PG8_SCHED;
;             PG8_LDA(At, 0, 1); PG8_STAGE(PG8_SB(0, 0), b2, voffB); PG8_STAGE(PG8_SB(0, 1), b2 + hstepB, voffB); PG8_STAGE(PG8_SA(0, 0), a2, voffA);
;             PG8_WAIT_V(8); PG8_WAIT_L(0); PG8_BAR; PG8_MMA(1, 0, At, B0); PG8_MMA(1, 1, At, B1); PG8_BAR; PG8_SCHED;
;             PG8_LDB(B0, 1, 0); PG8_LDB(B1, 1, 1); PG8_SCHED; PG8_LDA(At, 1, 0); PG8_STAGE(PG8_SA(0, 1), a2 + hstepA, voffA);
;             PG8_WAIT_V(8); PG8_WAIT_L(0); PG8_BAR; PG8_MMA(0, 0, At, B0); PG8_MMA(0, 1, At, B1); PG8_BAR; PG8_SCHED;
.LBB0_1511:
	ds_read_b128 v[18:21], v187
	ds_read_b128 v[26:29], v187 offset:2048
	ds_read_b128 v[22:25], v188
	ds_read_b128 v[30:33], v188 offset:2048
	ds_read_b128 v[2:5], v189
	ds_read_b128 v[10:13], v189 offset:2048
	ds_read_b128 v[6:9], v190
	ds_read_b128 v[14:17], v190 offset:2048
	s_add_i32 s82, s40, 2
	s_add_u32 s34, s38, 0xfff50080
	s_addc_u32 s35, s39, -1
	s_cmp_eq_u32 s79, s40
	s_cselect_b32 s40, s26, s34
	s_cselect_b32 s41, s27, s35
	s_cselect_b32 s35, s29, s81
	s_cselect_b32 s34, s28, s80
	s_add_i32 m0, s52, 0xc000
	ds_read_b128 v[174:177], v191
	ds_read_b128 v[194:197], v191 offset:2048
	ds_read_b128 v[178:181], v192
	ds_read_b128 v[198:201], v192 offset:2048
	ds_read_b128 v[202:205], v191 offset:4096
	ds_read_b128 v[210:213], v191 offset:6144
	ds_read_b128 v[206:209], v192 offset:4096
	ds_read_b128 v[214:217], v192 offset:6144
	global_load_lds_dwordx4 v170, s[38:39]
	s_add_i32 m0, s52, 0xe000
	s_nop 0
	global_load_lds_dwordx4 v172, s[38:39]
	s_waitcnt vmcnt(8)
	s_waitcnt lgkmcnt(0)
	s_barrier
	s_setprio 1
	s_waitcnt lgkmcnt(0)
	s_cmp_eq_u32 s100, 1
	s_cbranch_scc1 .Lcy5_0f
	v_mfma_scale_f32_16x16x128_f8f6f4 v[158:161], v[18:25], v[174:181], v[158:161], v1, v182 op_sel_hi:[0,0,0]
	v_mfma_scale_f32_16x16x128_f8f6f4 v[154:157], v[26:33], v[174:181], v[154:157], v1, v182 op_sel_hi:[0,0,0]
	v_mfma_scale_f32_16x16x128_f8f6f4 v[150:153], v[18:25], v[194:201], v[150:153], v1, v182 op_sel_hi:[0,0,0]
	v_mfma_scale_f32_16x16x128_f8f6f4 v[138:141], v[26:33], v[194:201], v[138:141], v1, v182 op_sel_hi:[0,0,0]
	v_mfma_scale_f32_16x16x128_f8f6f4 v[130:133], v[18:25], v[202:209], v[130:133], v1, v182 op_sel_hi:[0,0,0]
	v_mfma_scale_f32_16x16x128_f8f6f4 v[122:125], v[26:33], v[202:209], v[122:125], v1, v182 op_sel_hi:[0,0,0]
	v_mfma_scale_f32_16x16x128_f8f6f4 v[118:121], v[18:25], v[210:217], v[118:121], v1, v182 op_sel_hi:[0,0,0]
	v_mfma_scale_f32_16x16x128_f8f6f4 v[106:109], v[26:33], v[210:217], v[106:109], v1, v182 op_sel_hi:[0,0,0]
	s_setprio 0
	s_setprio 1
	v_mfma_scale_f32_16x16x128_f8f6f4 v[146:149], v[2:9], v[174:181], v[146:149], v1, v182 op_sel_hi:[0,0,0]
	v_mfma_scale_f32_16x16x128_f8f6f4 v[142:145], v[10:17], v[174:181], v[142:145], v1, v182 op_sel_hi:[0,0,0]
	v_mfma_scale_f32_16x16x128_f8f6f4 v[134:137], v[2:9], v[194:201], v[134:137], v1, v182 op_sel_hi:[0,0,0]
	v_mfma_scale_f32_16x16x128_f8f6f4 v[126:129], v[10:17], v[194:201], v[126:129], v1, v182 op_sel_hi:[0,0,0]
	v_mfma_scale_f32_16x16x128_f8f6f4 v[114:117], v[2:9], v[202:209], v[114:117], v1, v182 op_sel_hi:[0,0,0]
	v_mfma_scale_f32_16x16x128_f8f6f4 v[110:113], v[10:17], v[202:209], v[110:113], v1, v182 op_sel_hi:[0,0,0]
	v_mfma_scale_f32_16x16x128_f8f6f4 v[102:105], v[2:9], v[210:217], v[102:105], v1, v182 op_sel_hi:[0,0,0]
	v_mfma_scale_f32_16x16x128_f8f6f4 v[98:101], v[10:17], v[210:217], v[98:101], v1, v182 op_sel_hi:[0,0,0]
.Lcy5_0j:
	s_setprio 0
	s_barrier
	s_add_i32 s83, s63, s45
	s_mov_b32 m0, s83
	ds_read_b128 v[194:197], v191 offset:16384
	ds_read_b128 v[202:205], v191 offset:18432
	ds_read_b128 v[198:201], v192 offset:16384
	ds_read_b128 v[206:209], v192 offset:18432
	ds_read_b128 v[210:213], v191 offset:20480
	ds_read_b128 v[218:221], v191 offset:22528
	ds_read_b128 v[214:217], v192 offset:20480
	ds_read_b128 v[222:225], v192 offset:22528
	global_load_lds_dwordx4 v164, s[34:35]
	s_add_i32 m0, s83, 0x2000
	s_add_u32 s84, s34, 0xb0000
	s_addc_u32 s85, s35, 0
	s_add_i32 s83, s64, s45
	global_load_lds_dwordx4 v168, s[34:35]
	s_mov_b32 m0, s83
	s_nop 0
	global_load_lds_dwordx4 v164, s[84:85]
	s_add_i32 m0, s83, 0x2000
	s_nop 0
	global_load_lds_dwordx4 v168, s[84:85]
	s_mov_b32 m0, s52
	s_nop 0
	global_load_lds_dwordx4 v162, s[40:41]
	s_mov_b32 m0, s53
	s_nop 0
	global_load_lds_dwordx4 v166, s[40:41]
	s_waitcnt vmcnt(8)
	s_waitcnt lgkmcnt(0)
	s_barrier
	s_setprio 1
	s_waitcnt lgkmcnt(0)
	s_cmp_eq_u32 s100, 1
	s_cbranch_scc1 .Lcy5_1f
	v_mfma_scale_f32_16x16x128_f8f6f4 v[94:97], v[18:25], v[194:201], v[94:97], v1, v182 op_sel_hi:[0,0,0]
	v_mfma_scale_f32_16x16x128_f8f6f4 v[90:93], v[26:33], v[194:201], v[90:93], v1, v182 op_sel_hi:[0,0,0]
	v_mfma_scale_f32_16x16x128_f8f6f4 v[82:85], v[18:25], v[202:209], v[82:85], v1, v182 op_sel_hi:[0,0,0]
	v_mfma_scale_f32_16x16x128_f8f6f4 v[74:77], v[26:33], v[202:209], v[74:77], v1, v182 op_sel_hi:[0,0,0]
	v_mfma_scale_f32_16x16x128_f8f6f4 v[66:69], v[18:25], v[210:217], v[66:69], v1, v182 op_sel_hi:[0,0,0]
	v_mfma_scale_f32_16x16x128_f8f6f4 v[58:61], v[26:33], v[210:217], v[58:61], v1, v182 op_sel_hi:[0,0,0]
	v_mfma_scale_f32_16x16x128_f8f6f4 v[50:53], v[18:25], v[218:225], v[50:53], v1, v182 op_sel_hi:[0,0,0]
	v_mfma_scale_f32_16x16x128_f8f6f4 v[42:45], v[26:33], v[218:225], v[42:45], v1, v182 op_sel_hi:[0,0,0]
	s_setprio 0
	s_setprio 1
	v_mfma_scale_f32_16x16x128_f8f6f4 v[86:89], v[2:9], v[194:201], v[86:89], v1, v182 op_sel_hi:[0,0,0]
	v_mfma_scale_f32_16x16x128_f8f6f4 v[78:81], v[10:17], v[194:201], v[78:81], v1, v182 op_sel_hi:[0,0,0]
	v_mfma_scale_f32_16x16x128_f8f6f4 v[70:73], v[2:9], v[202:209], v[70:73], v1, v182 op_sel_hi:[0,0,0]
	v_mfma_scale_f32_16x16x128_f8f6f4 v[62:65], v[10:17], v[202:209], v[62:65], v1, v182 op_sel_hi:[0,0,0]
	v_mfma_scale_f32_16x16x128_f8f6f4 v[54:57], v[2:9], v[210:217], v[54:57], v1, v182 op_sel_hi:[0,0,0]
	v_mfma_scale_f32_16x16x128_f8f6f4 v[46:49], v[10:17], v[210:217], v[46:49], v1, v182 op_sel_hi:[0,0,0]
	v_mfma_scale_f32_16x16x128_f8f6f4 v[38:41], v[2:9], v[218:225], v[38:41], v1, v182 op_sel_hi:[0,0,0]
	v_mfma_scale_f32_16x16x128_f8f6f4 v[34:37], v[10:17], v[218:225], v[34:37], v1, v182 op_sel_hi:[0,0,0]
; #define PG8_STAGE(bufoff, gbase, voff) do { _Pragma("unroll") for (int _i = 0; _i < 2; ++_i) \
;         __builtin_amdgcn_global_load_lds((const unsigned*)((const char*)(gbase) + (voff)[_i]), (PG8_LAS unsigned*)(lds + (bufoff) + ldsw + _i * 8192), 16, 0, 0); } while (0)
; #define PG8_LDA(dst, b, h) do { _Pragma("unroll") for (int m = 0; m < 4; ++m) _Pragma("unroll") for (int k = 0; k < 2; ++k) dst[m][k] = *(const PG8_LAS bf16x8*)(lds + PG8_SA(b, h) + aoff + m * 2048 + k * 1024); } while (0)
; #define PG8_LDB(dst, b, h) do { _Pragma("unroll") for (int n = 0; n < 2; ++n) _Pragma("unroll") for (int k = 0; k < 2; ++k) dst[n][k] = *(const PG8_LAS bf16x8*)(lds + PG8_SB(b, h) + boff + n * 2048 + k * 1024); } while (0)
; #define PG8_MMA(ai, bj, At, Bt) do { __builtin_amdgcn_s_setprio(1); _Pragma("unroll") for (int m = 0; m < 4; ++m) _Pragma("unroll") for (int n = 0; n < 2; ++n) _Pragma("unroll") for (int k = 0; k < 2; ++k) \
;         acc[ai][bj][m][n] = __builtin_amdgcn_mfma_f32_16x16x32_bf16(Bt[n][k], At[m][k], acc[ai][bj][m][n], 0, 0, 0); __builtin_amdgcn_s_setprio(0); } while (0)
; #define PG8_WAIT_V(n) asm volatile("s_waitcnt vmcnt(" #n ")" ::: "memory")
; #define PG8_WAIT_L(n) asm volatile("s_waitcnt lgkmcnt(" #n ")" ::: "memory")
; #define PG8_BAR __builtin_amdgcn_s_barrier()
; #define PG8_SCHED __builtin_amdgcn_sched_barrier(0)
; #define PG8_STAGE(bufoff, gbase, voff) do { _Pragma("unroll") for (int _i = 0; _i < 2; ++_i) \
;         __builtin_amdgcn_global_load_lds((const unsigned*)((const char*)(gbase) + (voff)[_i]), (PG8_LAS unsigned*)(lds + (bufoff) + ldsw + _i * 8192), 16, 0, 0); } while (0)
; #define PG8_BAR __builtin_amdgcn_s_barrier()
; template <class Epi, class Sched, bool ALIGN_EPI = false>
; __device__ __forceinline__ void gemm_phase8(PG8_LAS unsigned char* lds, const Gemm g, const Sched& S, const Epi& E) {
;     ...
;             PG8_LDB(B0, 1, 0); PG8_LDB(B1, 1, 1); PG8_SCHED; PG8_LDA(At, 1, 0); PG8_STAGE(PG8_SA(0, 1), a2 + hstepA, voffA);
;             PG8_WAIT_V(8); PG8_WAIT_L(0); PG8_BAR; PG8_MMA(0, 0, At, B0); PG8_MMA(0, 1, At, B1); PG8_BAR; PG8_SCHED;
;             PG8_LDA(At, 1, 1); PG8_STAGE(PG8_SB(1, 0), b3, voffB); PG8_STAGE(PG8_SB(1, 1), b3 + hstepB, voffB); PG8_STAGE(PG8_SA(1, 0), a3, voffA);
;             PG8_WAIT_V(8); PG8_WAIT_L(0); PG8_BAR; PG8_MMA(1, 0, At, B0); PG8_MMA(1, 1, At, B1); PG8_BAR; PG8_SCHED;
;         }
.Lcy5_1j:
	s_setprio 0
	s_barrier
	s_add_i32 s83, 0, 0x18000
	s_add_i32 s84, 0, 0x1c000
	v_add_u32_e32 v6, s83, v184
	v_add_u32_e32 v14, s83, v185
	v_add_u32_e32 v22, s84, v184
	v_add_u32_e32 v30, s84, v185
	ds_read_b128 v[2:5], v6
	ds_read_b128 v[10:13], v6 offset:2048
	ds_read_b128 v[6:9], v14
	ds_read_b128 v[14:17], v14 offset:2048
	ds_read_b128 v[18:21], v22
	ds_read_b128 v[26:29], v22 offset:2048
	ds_read_b128 v[22:25], v30
	ds_read_b128 v[30:33], v30 offset:2048
	s_add_u32 s40, s40, 0xb0000
	s_addc_u32 s41, s41, 0
	s_mov_b32 m0, s54
	ds_read_b128 v[194:197], v191 offset:32768
	ds_read_b128 v[202:205], v191 offset:34816
	ds_read_b128 v[198:201], v192 offset:32768
	ds_read_b128 v[206:209], v192 offset:34816
	ds_read_b128 v[210:213], v191 offset:36864
	ds_read_b128 v[218:221], v191 offset:38912
	ds_read_b128 v[214:217], v192 offset:36864
	ds_read_b128 v[222:225], v192 offset:38912
	global_load_lds_dwordx4 v162, s[40:41]
	s_mov_b32 m0, s55
	s_nop 0
	global_load_lds_dwordx4 v166, s[40:41]
	s_waitcnt vmcnt(8)
	s_waitcnt lgkmcnt(0)
	s_barrier
	s_setprio 1
	s_waitcnt lgkmcnt(0)
	v_mfma_scale_f32_16x16x128_f8f6f4 v[158:161], v[2:9], v[194:201], v[158:161], v1, v182 op_sel_hi:[0,0,0]
	v_mfma_scale_f32_16x16x128_f8f6f4 v[154:157], v[10:17], v[194:201], v[154:157], v1, v182 op_sel_hi:[0,0,0]
	v_mfma_scale_f32_16x16x128_f8f6f4 v[150:153], v[2:9], v[202:209], v[150:153], v1, v182 op_sel_hi:[0,0,0]
	v_mfma_scale_f32_16x16x128_f8f6f4 v[138:141], v[10:17], v[202:209], v[138:141], v1, v182 op_sel_hi:[0,0,0]
	v_mfma_scale_f32_16x16x128_f8f6f4 v[130:133], v[2:9], v[210:217], v[130:133], v1, v182 op_sel_hi:[0,0,0]
	v_mfma_scale_f32_16x16x128_f8f6f4 v[122:125], v[10:17], v[210:217], v[122:125], v1, v182 op_sel_hi:[0,0,0]
	v_mfma_scale_f32_16x16x128_f8f6f4 v[118:121], v[2:9], v[218:225], v[118:121], v1, v182 op_sel_hi:[0,0,0]
	v_mfma_scale_f32_16x16x128_f8f6f4 v[106:109], v[10:17], v[218:225], v[106:109], v1, v182 op_sel_hi:[0,0,0]
	s_setprio 0
	s_setprio 1
	v_mfma_scale_f32_16x16x128_f8f6f4 v[146:149], v[18:25], v[194:201], v[146:149], v1, v182 op_sel_hi:[0,0,0]
	v_mfma_scale_f32_16x16x128_f8f6f4 v[142:145], v[26:33], v[194:201], v[142:145], v1, v182 op_sel_hi:[0,0,0]
	v_mfma_scale_f32_16x16x128_f8f6f4 v[134:137], v[18:25], v[202:209], v[134:137], v1, v182 op_sel_hi:[0,0,0]
	v_mfma_scale_f32_16x16x128_f8f6f4 v[126:129], v[26:33], v[202:209], v[126:129], v1, v182 op_sel_hi:[0,0,0]
	v_mfma_scale_f32_16x16x128_f8f6f4 v[114:117], v[18:25], v[210:217], v[114:117], v1, v182 op_sel_hi:[0,0,0]
	v_mfma_scale_f32_16x16x128_f8f6f4 v[110:113], v[26:33], v[210:217], v[110:113], v1, v182 op_sel_hi:[0,0,0]
	v_mfma_scale_f32_16x16x128_f8f6f4 v[102:105], v[18:25], v[218:225], v[102:105], v1, v182 op_sel_hi:[0,0,0]
	v_mfma_scale_f32_16x16x128_f8f6f4 v[98:101], v[26:33], v[218:225], v[98:101], v1, v182 op_sel_hi:[0,0,0]
	s_setprio 0
	s_barrier
	s_add_i32 s101, s83, s45
	s_add_u32 s98, s34, s12
	s_addc_u32 s99, s35, s13
	s_mov_b32 m0, s101
	ds_read_b128 v[194:197], v191 offset:49152
	ds_read_b128 v[202:205], v191 offset:51200
	ds_read_b128 v[198:201], v192 offset:49152
	ds_read_b128 v[206:209], v192 offset:51200
	ds_read_b128 v[210:213], v191 offset:53248
	ds_read_b128 v[218:221], v191 offset:55296
	ds_read_b128 v[214:217], v192 offset:53248
	ds_read_b128 v[222:225], v192 offset:55296
	global_load_lds_dwordx4 v164, s[98:99]
	s_add_i32 m0, s101, 0x2000
	s_add_u32 s34, s34, 0xb0080
	s_addc_u32 s35, s35, 0
	s_add_i32 s101, s84, s45
	global_load_lds_dwordx4 v168, s[98:99]
	s_add_u32 s98, s40, s12
	s_addc_u32 s99, s41, s13
	s_sub_u32 s98, s98, 0xb0000
	s_subb_u32 s99, s99, 0
	s_mov_b32 m0, s101
	s_nop 0
	global_load_lds_dwordx4 v164, s[34:35]
	s_add_i32 m0, s101, 0x2000
	s_nop 0
	global_load_lds_dwordx4 v168, s[34:35]
	s_mov_b32 m0, s61
	s_nop 0
	global_load_lds_dwordx4 v162, s[98:99]
	s_mov_b32 m0, s62
	s_nop 0
	global_load_lds_dwordx4 v166, s[98:99]
	s_waitcnt vmcnt(8)
	s_waitcnt lgkmcnt(0)
	s_barrier
	s_setprio 1
	s_waitcnt lgkmcnt(0)
	v_mfma_scale_f32_16x16x128_f8f6f4 v[94:97], v[2:9], v[194:201], v[94:97], v1, v182 op_sel_hi:[0,0,0]
	v_mfma_scale_f32_16x16x128_f8f6f4 v[90:93], v[10:17], v[194:201], v[90:93], v1, v182 op_sel_hi:[0,0,0]
	v_mfma_scale_f32_16x16x128_f8f6f4 v[82:85], v[2:9], v[202:209], v[82:85], v1, v182 op_sel_hi:[0,0,0]
	v_mfma_scale_f32_16x16x128_f8f6f4 v[74:77], v[10:17], v[202:209], v[74:77], v1, v182 op_sel_hi:[0,0,0]
	v_mfma_scale_f32_16x16x128_f8f6f4 v[66:69], v[2:9], v[210:217], v[66:69], v1, v182 op_sel_hi:[0,0,0]
	v_mfma_scale_f32_16x16x128_f8f6f4 v[58:61], v[10:17], v[210:217], v[58:61], v1, v182 op_sel_hi:[0,0,0]
	v_mfma_scale_f32_16x16x128_f8f6f4 v[50:53], v[2:9], v[218:225], v[50:53], v1, v182 op_sel_hi:[0,0,0]
	v_mfma_scale_f32_16x16x128_f8f6f4 v[42:45], v[10:17], v[218:225], v[42:45], v1, v182 op_sel_hi:[0,0,0]
	s_setprio 0
	s_setprio 1
	v_mfma_scale_f32_16x16x128_f8f6f4 v[86:89], v[18:25], v[194:201], v[86:89], v1, v182 op_sel_hi:[0,0,0]
	v_mfma_scale_f32_16x16x128_f8f6f4 v[78:81], v[26:33], v[194:201], v[78:81], v1, v182 op_sel_hi:[0,0,0]
	v_mfma_scale_f32_16x16x128_f8f6f4 v[70:73], v[18:25], v[202:209], v[70:73], v1, v182 op_sel_hi:[0,0,0]
	v_mfma_scale_f32_16x16x128_f8f6f4 v[62:65], v[26:33], v[202:209], v[62:65], v1, v182 op_sel_hi:[0,0,0]
	v_mfma_scale_f32_16x16x128_f8f6f4 v[54:57], v[18:25], v[210:217], v[54:57], v1, v182 op_sel_hi:[0,0,0]
	v_mfma_scale_f32_16x16x128_f8f6f4 v[46:49], v[26:33], v[210:217], v[46:49], v1, v182 op_sel_hi:[0,0,0]
	v_mfma_scale_f32_16x16x128_f8f6f4 v[38:41], v[18:25], v[218:225], v[38:41], v1, v182 op_sel_hi:[0,0,0]
	v_mfma_scale_f32_16x16x128_f8f6f4 v[34:37], v[26:33], v[218:225], v[34:37], v1, v182 op_sel_hi:[0,0,0]
	s_setprio 0
	s_barrier
	s_add_u32 s38, s38, 0x100
	s_addc_u32 s39, s39, 0
	s_add_u32 s80, s80, 0x100
	s_addc_u32 s81, s81, 0
	s_cmp_ge_u32 s82, s31
	s_mov_b32 s40, s82
	s_cbranch_scc0 .LBB0_1511
	s_and_b64 vcc, exec, s[14:15]
	s_cbranch_vccz .LBB0_1514
	s_barrier
